# adds: attn_sample second 64-key group: the 8 key quads of the first loop trip requested together
# speedup vs baseline: 1.0052x; 1.0052x over previous
; #define LAS __attribute__((address_space(3)))
; __device__ __forceinline__ void attn_sample_wave(const Frame& F, int unit) {
;     ...
;     for (int kk = 0; kk < 3; ++kk) { const int kidx = kk * 64 + lane;
; #pragma unroll
;         for (int t = 0; t < 4; ++t) sc[kk][t] = 0.f;
;         if (kidx < 128) { const f32x4* kr = (const f32x4*)(F.in[2] + ((size_t)b * 128 + kidx) * 256 + g * 64);
; #pragma unroll 8
;             for (int d4 = 0; d4 < 16; ++d4) { const f32x4 kv = kr[d4];
; #pragma unroll
;                 for (int t = 0; t < 4; ++t) { const f32x4 q = *(const LAS f32x4*)(sq + t * 64 + d4 * 4); sc[kk][t] += kv[0] * q[0] + kv[1] * q[1] + kv[2] * q[2] + kv[3] * q[3]; } } }
.LBB0_510:
	v_lshl_add_u64 v[82:83], v[22:23], 0, vcc
	s_waitcnt vmcnt(0)
	v_mov_b32_e32 v24, v112
	v_mov_b32_e32 v25, v113
	v_mov_b32_e32 v26, v114
	v_mov_b32_e32 v27, v115
	v_mov_b32_e32 v28, v108
	v_mov_b32_e32 v29, v109
	v_mov_b32_e32 v30, v110
	v_mov_b32_e32 v31, v111
	v_mov_b32_e32 v32, v104
	v_mov_b32_e32 v33, v105
	v_mov_b32_e32 v34, v106
	v_mov_b32_e32 v35, v107
	v_mov_b32_e32 v36, v100
	v_mov_b32_e32 v37, v101
	v_mov_b32_e32 v38, v102
	v_mov_b32_e32 v39, v103
	v_mov_b32_e32 v86, s28
	ds_read_b128 v[62:65], v86
	ds_read_b128 v[66:69], v86 offset:16
	ds_read_b128 v[70:73], v86 offset:32
	ds_read_b128 v[74:77], v86 offset:48
	ds_read_b128 v[78:81], v86 offset:256
	s_waitcnt lgkmcnt(4)
	v_mov_b32_e32 v85, v63
	s_addk_i32 s28, 0x80
	s_add_u32 vcc_lo, vcc_lo, 0x80
	s_addc_u32 vcc_hi, vcc_hi, 0
	s_waitcnt lgkmcnt(0)
	v_mov_b32_e32 v84, v78
	v_mov_b32_e32 v78, v79
	v_mov_b32_e32 v79, v62
	s_cmpk_lg_i32 vcc_lo, 0x100
	s_waitcnt vmcnt(0)
	v_pk_mul_f32 v[84:85], v[36:37], v[84:85]
	s_nop 0
	v_pk_fma_f32 v[62:63], v[36:37], v[78:79], v[84:85] op_sel:[1,0,0] op_sel_hi:[0,1,1]
	v_mov_b32_e32 v78, v80
	v_mov_b32_e32 v79, v64
	v_pk_fma_f32 v[62:63], v[38:39], v[78:79], v[62:63] op_sel_hi:[0,1,1]
	v_mov_b32_e32 v4, v39
	v_mov_b32_e32 v64, v81
	v_pk_fma_f32 v[62:63], v[4:5], v[64:65], v[62:63] op_sel_hi:[0,1,1]
	v_pk_add_f32 v[84:85], v[2:3], v[62:63]
	ds_read_b128 v[62:65], v86 offset:512
	ds_read_b128 v[78:81], v86 offset:768
	s_waitcnt lgkmcnt(1)
	v_mov_b32_e32 v3, v63
	s_waitcnt lgkmcnt(0)
	v_mov_b32_e32 v2, v78
	v_pk_mul_f32 v[2:3], v[36:37], v[2:3]
	v_mov_b32_e32 v78, v79
	v_mov_b32_e32 v79, v62
	v_pk_fma_f32 v[2:3], v[36:37], v[78:79], v[2:3] op_sel:[1,0,0] op_sel_hi:[0,1,1]
	v_mov_b32_e32 v36, v80
	v_mov_b32_e32 v37, v64
	v_pk_fma_f32 v[2:3], v[38:39], v[36:37], v[2:3] op_sel_hi:[0,1,1]
	v_mov_b32_e32 v64, v81
	v_pk_fma_f32 v[2:3], v[4:5], v[64:65], v[2:3] op_sel_hi:[0,1,1]
	v_pk_add_f32 v[62:63], v[0:1], v[2:3]
	ds_read_b128 v[0:3], v86 offset:272
	v_mov_b32_e32 v37, v67
	v_mov_b32_e32 v4, v35
	s_waitcnt lgkmcnt(0)
	v_mov_b32_e32 v36, v0
	v_pk_mul_f32 v[36:37], v[32:33], v[36:37]
	v_mov_b32_e32 v0, v1
	v_mov_b32_e32 v1, v66
	v_pk_fma_f32 v[0:1], v[32:33], v[0:1], v[36:37] op_sel:[1,0,0] op_sel_hi:[0,1,1]
	v_mov_b32_e32 v36, v2
	v_mov_b32_e32 v37, v68
	v_pk_fma_f32 v[0:1], v[34:35], v[36:37], v[0:1] op_sel_hi:[0,1,1]
	v_mov_b32_e32 v68, v3
	v_pk_fma_f32 v[0:1], v[4:5], v[68:69], v[0:1] op_sel_hi:[0,1,1]
	v_pk_add_f32 v[64:65], v[84:85], v[0:1]
	ds_read_b128 v[0:3], v86 offset:528
	ds_read_b128 v[36:39], v86 offset:784
	s_waitcnt lgkmcnt(1)
	v_mov_b32_e32 v67, v1
	s_waitcnt lgkmcnt(0)
	v_mov_b32_e32 v66, v36
	v_pk_mul_f32 v[66:67], v[32:33], v[66:67]
	v_mov_b32_e32 v36, v37
	v_mov_b32_e32 v37, v0
	v_pk_fma_f32 v[0:1], v[32:33], v[36:37], v[66:67] op_sel:[1,0,0] op_sel_hi:[0,1,1]
	v_mov_b32_e32 v32, v38
	v_mov_b32_e32 v33, v2
	v_pk_fma_f32 v[0:1], v[34:35], v[32:33], v[0:1] op_sel_hi:[0,1,1]
	v_mov_b32_e32 v2, v39
	v_pk_fma_f32 v[0:1], v[4:5], v[2:3], v[0:1] op_sel_hi:[0,1,1]
	v_pk_add_f32 v[36:37], v[62:63], v[0:1]
	ds_read_b128 v[0:3], v86 offset:288
	v_mov_b32_e32 v33, v71
	v_mov_b32_e32 v4, v31
	s_waitcnt lgkmcnt(0)
	v_mov_b32_e32 v32, v0
	v_pk_mul_f32 v[32:33], v[28:29], v[32:33]
	v_mov_b32_e32 v0, v1
	v_mov_b32_e32 v1, v70
	v_pk_fma_f32 v[0:1], v[28:29], v[0:1], v[32:33] op_sel:[1,0,0] op_sel_hi:[0,1,1]
	v_mov_b32_e32 v32, v2
	v_mov_b32_e32 v33, v72
	v_pk_fma_f32 v[0:1], v[30:31], v[32:33], v[0:1] op_sel_hi:[0,1,1]
	v_mov_b32_e32 v72, v3
	v_pk_fma_f32 v[0:1], v[4:5], v[72:73], v[0:1] op_sel_hi:[0,1,1]
	v_pk_add_f32 v[38:39], v[64:65], v[0:1]
	ds_read_b128 v[0:3], v86 offset:544
	ds_read_b128 v[32:35], v86 offset:800
	s_waitcnt lgkmcnt(1)
	v_mov_b32_e32 v63, v1
	s_waitcnt lgkmcnt(0)
	v_mov_b32_e32 v62, v32
	v_pk_mul_f32 v[62:63], v[28:29], v[62:63]
	v_mov_b32_e32 v32, v33
	v_mov_b32_e32 v33, v0
	v_pk_fma_f32 v[0:1], v[28:29], v[32:33], v[62:63] op_sel:[1,0,0] op_sel_hi:[0,1,1]
	v_mov_b32_e32 v28, v34
	v_mov_b32_e32 v29, v2
	v_pk_fma_f32 v[0:1], v[30:31], v[28:29], v[0:1] op_sel_hi:[0,1,1]
	v_mov_b32_e32 v2, v35
	v_pk_fma_f32 v[0:1], v[4:5], v[2:3], v[0:1] op_sel_hi:[0,1,1]
	v_pk_add_f32 v[32:33], v[36:37], v[0:1]
	ds_read_b128 v[0:3], v86 offset:304
	v_mov_b32_e32 v29, v75
	v_mov_b32_e32 v4, v27
	s_waitcnt lgkmcnt(0)
	v_mov_b32_e32 v28, v0
	v_pk_mul_f32 v[28:29], v[24:25], v[28:29]
	v_mov_b32_e32 v0, v1
	v_mov_b32_e32 v1, v74
	v_pk_fma_f32 v[0:1], v[24:25], v[0:1], v[28:29] op_sel:[1,0,0] op_sel_hi:[0,1,1]
	v_mov_b32_e32 v28, v2
	v_mov_b32_e32 v29, v76
	v_pk_fma_f32 v[0:1], v[26:27], v[28:29], v[0:1] op_sel_hi:[0,1,1]
	v_mov_b32_e32 v76, v3
	v_pk_fma_f32 v[0:1], v[4:5], v[76:77], v[0:1] op_sel_hi:[0,1,1]
	v_pk_add_f32 v[66:67], v[38:39], v[0:1]
	ds_read_b128 v[0:3], v86 offset:560
	ds_read_b128 v[28:31], v86 offset:816
	s_waitcnt lgkmcnt(1)
	v_mov_b32_e32 v35, v1
	s_waitcnt lgkmcnt(0)
	v_mov_b32_e32 v34, v28
	v_pk_mul_f32 v[34:35], v[24:25], v[34:35]
	v_mov_b32_e32 v28, v29
	v_mov_b32_e32 v29, v0
	v_pk_fma_f32 v[0:1], v[24:25], v[28:29], v[34:35] op_sel:[1,0,0] op_sel_hi:[0,1,1]
	v_mov_b32_e32 v24, v30
	v_mov_b32_e32 v25, v2
	v_pk_fma_f32 v[0:1], v[26:27], v[24:25], v[0:1] op_sel_hi:[0,1,1]
	v_mov_b32_e32 v2, v31
	v_pk_fma_f32 v[0:1], v[4:5], v[2:3], v[0:1] op_sel_hi:[0,1,1]
	v_pk_add_f32 v[68:69], v[32:33], v[0:1]
	v_mov_b32_e32 v24, v128
	v_mov_b32_e32 v25, v129
	v_mov_b32_e32 v26, v130
	v_mov_b32_e32 v27, v131
	v_mov_b32_e32 v0, v124
	v_mov_b32_e32 v1, v125
	v_mov_b32_e32 v2, v126
	v_mov_b32_e32 v3, v127
	v_mov_b32_e32 v28, v120
	v_mov_b32_e32 v29, v121
	v_mov_b32_e32 v30, v122
	v_mov_b32_e32 v31, v123
	v_mov_b32_e32 v32, v116
	v_mov_b32_e32 v33, v117
	v_mov_b32_e32 v34, v118
	v_mov_b32_e32 v35, v119
	ds_read_b128 v[36:39], v86 offset:64
	ds_read_b128 v[62:65], v86 offset:320
	s_waitcnt lgkmcnt(1)
; #define LAS __attribute__((address_space(3)))
; __device__ __forceinline__ void attn_sample_wave(const Frame& F, int unit) {
;     ...
;     for (int kk = 0; kk < 3; ++kk) { const int kidx = kk * 64 + lane;
; #pragma unroll
;         for (int t = 0; t < 4; ++t) sc[kk][t] = 0.f;
;         if (kidx < 128) { const f32x4* kr = (const f32x4*)(F.in[2] + ((size_t)b * 128 + kidx) * 256 + g * 64);
; #pragma unroll 8
;             for (int d4 = 0; d4 < 16; ++d4) { const f32x4 kv = kr[d4];
; #pragma unroll
;                 for (int t = 0; t < 4; ++t) { const f32x4 q = *(const LAS f32x4*)(sq + t * 64 + d4 * 4); sc[kk][t] += kv[0] * q[0] + kv[1] * q[1] + kv[2] * q[2] + kv[3] * q[3]; } } }
	v_mov_b32_e32 v71, v37
	s_waitcnt lgkmcnt(0)
	v_mov_b32_e32 v70, v62
	v_mov_b32_e32 v62, v63
	v_mov_b32_e32 v63, v36
	s_waitcnt vmcnt(0)
	v_pk_mul_f32 v[70:71], v[32:33], v[70:71]
	s_nop 0
	v_pk_fma_f32 v[36:37], v[32:33], v[62:63], v[70:71] op_sel:[1,0,0] op_sel_hi:[0,1,1]
	v_mov_b32_e32 v62, v64
	v_mov_b32_e32 v63, v38
	v_pk_fma_f32 v[36:37], v[34:35], v[62:63], v[36:37] op_sel_hi:[0,1,1]
	v_mov_b32_e32 v4, v35
	v_mov_b32_e32 v38, v65
	v_pk_fma_f32 v[36:37], v[4:5], v[38:39], v[36:37] op_sel_hi:[0,1,1]
	v_pk_add_f32 v[66:67], v[66:67], v[36:37]
	ds_read_b128 v[36:39], v86 offset:576
	ds_read_b128 v[62:65], v86 offset:832
	s_waitcnt lgkmcnt(1)
	v_mov_b32_e32 v71, v37
	s_waitcnt lgkmcnt(0)
	v_mov_b32_e32 v70, v62
	v_pk_mul_f32 v[70:71], v[32:33], v[70:71]
	v_mov_b32_e32 v62, v63
	v_mov_b32_e32 v63, v36
	v_pk_fma_f32 v[32:33], v[32:33], v[62:63], v[70:71] op_sel:[1,0,0] op_sel_hi:[0,1,1]
	v_mov_b32_e32 v36, v64
	v_mov_b32_e32 v37, v38
	v_pk_fma_f32 v[32:33], v[34:35], v[36:37], v[32:33] op_sel_hi:[0,1,1]
	v_mov_b32_e32 v38, v65
	v_pk_fma_f32 v[32:33], v[4:5], v[38:39], v[32:33] op_sel_hi:[0,1,1]
	v_pk_add_f32 v[62:63], v[68:69], v[32:33]
	ds_read_b128 v[32:35], v86 offset:80
	ds_read_b128 v[36:39], v86 offset:336
	v_mov_b32_e32 v4, v31
	s_waitcnt lgkmcnt(1)
	v_mov_b32_e32 v65, v33
	s_waitcnt lgkmcnt(0)
	v_mov_b32_e32 v64, v36
	v_pk_mul_f32 v[64:65], v[28:29], v[64:65]
	v_mov_b32_e32 v36, v37
	v_mov_b32_e32 v37, v32
	v_pk_fma_f32 v[32:33], v[28:29], v[36:37], v[64:65] op_sel:[1,0,0] op_sel_hi:[0,1,1]
	v_mov_b32_e32 v36, v38
	v_mov_b32_e32 v37, v34
	v_pk_fma_f32 v[32:33], v[30:31], v[36:37], v[32:33] op_sel_hi:[0,1,1]
	v_mov_b32_e32 v34, v39
	v_pk_fma_f32 v[32:33], v[4:5], v[34:35], v[32:33] op_sel_hi:[0,1,1]
	v_pk_add_f32 v[64:65], v[66:67], v[32:33]
	ds_read_b128 v[32:35], v86 offset:592
	ds_read_b128 v[36:39], v86 offset:848
	s_waitcnt lgkmcnt(1)
	v_mov_b32_e32 v67, v33
	s_waitcnt lgkmcnt(0)
	v_mov_b32_e32 v66, v36
	v_pk_mul_f32 v[66:67], v[28:29], v[66:67]
	v_mov_b32_e32 v36, v37
	v_mov_b32_e32 v37, v32
	v_pk_fma_f32 v[28:29], v[28:29], v[36:37], v[66:67] op_sel:[1,0,0] op_sel_hi:[0,1,1]
	v_mov_b32_e32 v32, v38
	v_mov_b32_e32 v33, v34
	v_pk_fma_f32 v[28:29], v[30:31], v[32:33], v[28:29] op_sel_hi:[0,1,1]
	v_mov_b32_e32 v34, v39
	v_pk_fma_f32 v[28:29], v[4:5], v[34:35], v[28:29] op_sel_hi:[0,1,1]
	v_pk_add_f32 v[36:37], v[62:63], v[28:29]
	ds_read_b128 v[28:31], v86 offset:96
	ds_read_b128 v[32:35], v86 offset:352
	v_mov_b32_e32 v4, v3
	s_waitcnt lgkmcnt(1)
	v_mov_b32_e32 v39, v29
	s_waitcnt lgkmcnt(0)
	v_mov_b32_e32 v38, v32
	v_pk_mul_f32 v[38:39], v[0:1], v[38:39]
	v_mov_b32_e32 v32, v33
	v_mov_b32_e32 v33, v28
	v_pk_fma_f32 v[28:29], v[0:1], v[32:33], v[38:39] op_sel:[1,0,0] op_sel_hi:[0,1,1]
	v_mov_b32_e32 v32, v34
	v_mov_b32_e32 v33, v30
	v_pk_fma_f32 v[28:29], v[2:3], v[32:33], v[28:29] op_sel_hi:[0,1,1]
	v_mov_b32_e32 v30, v35
	v_pk_fma_f32 v[28:29], v[4:5], v[30:31], v[28:29] op_sel_hi:[0,1,1]
	v_pk_add_f32 v[38:39], v[64:65], v[28:29]
	ds_read_b128 v[28:31], v86 offset:608
	ds_read_b128 v[32:35], v86 offset:864
	s_waitcnt lgkmcnt(1)
	v_mov_b32_e32 v63, v29
	s_waitcnt lgkmcnt(0)
	v_mov_b32_e32 v62, v32
	v_pk_mul_f32 v[62:63], v[0:1], v[62:63]
	v_mov_b32_e32 v32, v33
	v_mov_b32_e32 v33, v28
	v_pk_fma_f32 v[0:1], v[0:1], v[32:33], v[62:63] op_sel:[1,0,0] op_sel_hi:[0,1,1]
	v_mov_b32_e32 v28, v34
	v_mov_b32_e32 v29, v30
	v_pk_fma_f32 v[0:1], v[2:3], v[28:29], v[0:1] op_sel_hi:[0,1,1]
	v_mov_b32_e32 v30, v35
	v_pk_fma_f32 v[0:1], v[4:5], v[30:31], v[0:1] op_sel_hi:[0,1,1]
	v_pk_add_f32 v[36:37], v[36:37], v[0:1]
	ds_read_b128 v[0:3], v86 offset:112
	ds_read_b128 v[28:31], v86 offset:368
	v_mov_b32_e32 v4, v27
	s_waitcnt lgkmcnt(1)
	v_mov_b32_e32 v33, v1
	s_waitcnt lgkmcnt(0)
	v_mov_b32_e32 v32, v28
	v_pk_mul_f32 v[32:33], v[24:25], v[32:33]
	v_mov_b32_e32 v28, v29
	v_mov_b32_e32 v29, v0
	v_pk_fma_f32 v[0:1], v[24:25], v[28:29], v[32:33] op_sel:[1,0,0] op_sel_hi:[0,1,1]
	v_mov_b32_e32 v28, v30
	v_mov_b32_e32 v29, v2
	v_pk_fma_f32 v[0:1], v[26:27], v[28:29], v[0:1] op_sel_hi:[0,1,1]
	v_mov_b32_e32 v2, v31
	ds_read_b128 v[28:31], v86 offset:624
	ds_read_b128 v[32:35], v86 offset:880
	v_pk_fma_f32 v[0:1], v[4:5], v[2:3], v[0:1] op_sel_hi:[0,1,1]
	v_pk_add_f32 v[2:3], v[38:39], v[0:1]
	s_waitcnt lgkmcnt(1)
	v_mov_b32_e32 v1, v29
	s_waitcnt lgkmcnt(0)
	v_mov_b32_e32 v0, v32
	v_pk_mul_f32 v[0:1], v[24:25], v[0:1]
	v_mov_b32_e32 v32, v33
	v_mov_b32_e32 v33, v28
	v_pk_fma_f32 v[0:1], v[24:25], v[32:33], v[0:1] op_sel:[1,0,0] op_sel_hi:[0,1,1]
	v_mov_b32_e32 v24, v34
	v_mov_b32_e32 v25, v30
	v_pk_fma_f32 v[0:1], v[26:27], v[24:25], v[0:1] op_sel_hi:[0,1,1]
	v_mov_b32_e32 v30, v35
	v_pk_fma_f32 v[0:1], v[4:5], v[30:31], v[0:1] op_sel_hi:[0,1,1]
	v_pk_add_f32 v[0:1], v[36:37], v[0:1]
	v_lshl_add_u64 v[82:83], v[22:23], 0, vcc
	v_mov_b32_e32 v24, v174
	v_mov_b32_e32 v25, v175
	v_mov_b32_e32 v26, v176
	v_mov_b32_e32 v27, v177
	v_mov_b32_e32 v28, v170
	v_mov_b32_e32 v29, v171
	v_mov_b32_e32 v30, v172
	v_mov_b32_e32 v31, v173
	v_mov_b32_e32 v32, v166
	v_mov_b32_e32 v33, v167
	v_mov_b32_e32 v34, v168
	v_mov_b32_e32 v35, v169
	v_mov_b32_e32 v36, v162
	v_mov_b32_e32 v37, v163
	v_mov_b32_e32 v38, v164
	v_mov_b32_e32 v39, v165
	v_mov_b32_e32 v86, s28
	ds_read_b128 v[62:65], v86
	ds_read_b128 v[66:69], v86 offset:16
	ds_read_b128 v[70:73], v86 offset:32
	ds_read_b128 v[74:77], v86 offset:48
	ds_read_b128 v[78:81], v86 offset:256
	s_waitcnt lgkmcnt(4)
	v_mov_b32_e32 v85, v63
	s_addk_i32 s28, 0x80
	s_add_u32 vcc_lo, vcc_lo, 0x80
	s_addc_u32 vcc_hi, vcc_hi, 0
	s_waitcnt lgkmcnt(0)
	v_mov_b32_e32 v84, v78
	v_mov_b32_e32 v78, v79
	v_mov_b32_e32 v79, v62
	s_cmpk_lg_i32 vcc_lo, 0x100
	s_waitcnt vmcnt(0)
; #define LAS __attribute__((address_space(3)))
; __device__ __forceinline__ void attn_sample_wave(const Frame& F, int unit) {
;     ...
;     for (int kk = 0; kk < 3; ++kk) { const int kidx = kk * 64 + lane;
; #pragma unroll
;         for (int t = 0; t < 4; ++t) sc[kk][t] = 0.f;
;         if (kidx < 128) { const f32x4* kr = (const f32x4*)(F.in[2] + ((size_t)b * 128 + kidx) * 256 + g * 64);
; #pragma unroll 8
;             for (int d4 = 0; d4 < 16; ++d4) { const f32x4 kv = kr[d4];
; #pragma unroll
;                 for (int t = 0; t < 4; ++t) { const f32x4 q = *(const LAS f32x4*)(sq + t * 64 + d4 * 4); sc[kk][t] += kv[0] * q[0] + kv[1] * q[1] + kv[2] * q[2] + kv[3] * q[3]; } } }
	v_pk_mul_f32 v[84:85], v[36:37], v[84:85]
	s_nop 0
	v_pk_fma_f32 v[62:63], v[36:37], v[78:79], v[84:85] op_sel:[1,0,0] op_sel_hi:[0,1,1]
	v_mov_b32_e32 v78, v80
	v_mov_b32_e32 v79, v64
	v_pk_fma_f32 v[62:63], v[38:39], v[78:79], v[62:63] op_sel_hi:[0,1,1]
	v_mov_b32_e32 v4, v39
	v_mov_b32_e32 v64, v81
	v_pk_fma_f32 v[62:63], v[4:5], v[64:65], v[62:63] op_sel_hi:[0,1,1]
	v_pk_add_f32 v[84:85], v[2:3], v[62:63]
	ds_read_b128 v[62:65], v86 offset:512
	ds_read_b128 v[78:81], v86 offset:768
	s_waitcnt lgkmcnt(1)
	v_mov_b32_e32 v3, v63
	s_waitcnt lgkmcnt(0)
	v_mov_b32_e32 v2, v78
	v_pk_mul_f32 v[2:3], v[36:37], v[2:3]
	v_mov_b32_e32 v78, v79
	v_mov_b32_e32 v79, v62
	v_pk_fma_f32 v[2:3], v[36:37], v[78:79], v[2:3] op_sel:[1,0,0] op_sel_hi:[0,1,1]
	v_mov_b32_e32 v36, v80
	v_mov_b32_e32 v37, v64
	v_pk_fma_f32 v[2:3], v[38:39], v[36:37], v[2:3] op_sel_hi:[0,1,1]
	v_mov_b32_e32 v64, v81
	v_pk_fma_f32 v[2:3], v[4:5], v[64:65], v[2:3] op_sel_hi:[0,1,1]
	v_pk_add_f32 v[62:63], v[0:1], v[2:3]
	ds_read_b128 v[0:3], v86 offset:272
	v_mov_b32_e32 v37, v67
	v_mov_b32_e32 v4, v35
	s_waitcnt lgkmcnt(0)
	v_mov_b32_e32 v36, v0
	v_pk_mul_f32 v[36:37], v[32:33], v[36:37]
	v_mov_b32_e32 v0, v1
	v_mov_b32_e32 v1, v66
	v_pk_fma_f32 v[0:1], v[32:33], v[0:1], v[36:37] op_sel:[1,0,0] op_sel_hi:[0,1,1]
	v_mov_b32_e32 v36, v2
	v_mov_b32_e32 v37, v68
	v_pk_fma_f32 v[0:1], v[34:35], v[36:37], v[0:1] op_sel_hi:[0,1,1]
	v_mov_b32_e32 v68, v3
	v_pk_fma_f32 v[0:1], v[4:5], v[68:69], v[0:1] op_sel_hi:[0,1,1]
	v_pk_add_f32 v[64:65], v[84:85], v[0:1]
	ds_read_b128 v[0:3], v86 offset:528
	ds_read_b128 v[36:39], v86 offset:784
	s_waitcnt lgkmcnt(1)
	v_mov_b32_e32 v67, v1
	s_waitcnt lgkmcnt(0)
	v_mov_b32_e32 v66, v36
	v_pk_mul_f32 v[66:67], v[32:33], v[66:67]
	v_mov_b32_e32 v36, v37
	v_mov_b32_e32 v37, v0
	v_pk_fma_f32 v[0:1], v[32:33], v[36:37], v[66:67] op_sel:[1,0,0] op_sel_hi:[0,1,1]
	v_mov_b32_e32 v32, v38
	v_mov_b32_e32 v33, v2
	v_pk_fma_f32 v[0:1], v[34:35], v[32:33], v[0:1] op_sel_hi:[0,1,1]
	v_mov_b32_e32 v2, v39
	v_pk_fma_f32 v[0:1], v[4:5], v[2:3], v[0:1] op_sel_hi:[0,1,1]
	v_pk_add_f32 v[36:37], v[62:63], v[0:1]
	ds_read_b128 v[0:3], v86 offset:288
	v_mov_b32_e32 v33, v71
	v_mov_b32_e32 v4, v31
	s_waitcnt lgkmcnt(0)
	v_mov_b32_e32 v32, v0
	v_pk_mul_f32 v[32:33], v[28:29], v[32:33]
	v_mov_b32_e32 v0, v1
	v_mov_b32_e32 v1, v70
	v_pk_fma_f32 v[0:1], v[28:29], v[0:1], v[32:33] op_sel:[1,0,0] op_sel_hi:[0,1,1]
	v_mov_b32_e32 v32, v2
	v_mov_b32_e32 v33, v72
	v_pk_fma_f32 v[0:1], v[30:31], v[32:33], v[0:1] op_sel_hi:[0,1,1]
	v_mov_b32_e32 v72, v3
	v_pk_fma_f32 v[0:1], v[4:5], v[72:73], v[0:1] op_sel_hi:[0,1,1]
	v_pk_add_f32 v[38:39], v[64:65], v[0:1]
	ds_read_b128 v[0:3], v86 offset:544
	ds_read_b128 v[32:35], v86 offset:800
	s_waitcnt lgkmcnt(1)
	v_mov_b32_e32 v63, v1
	s_waitcnt lgkmcnt(0)
	v_mov_b32_e32 v62, v32
	v_pk_mul_f32 v[62:63], v[28:29], v[62:63]
	v_mov_b32_e32 v32, v33
	v_mov_b32_e32 v33, v0
	v_pk_fma_f32 v[0:1], v[28:29], v[32:33], v[62:63] op_sel:[1,0,0] op_sel_hi:[0,1,1]
	v_mov_b32_e32 v28, v34
	v_mov_b32_e32 v29, v2
	v_pk_fma_f32 v[0:1], v[30:31], v[28:29], v[0:1] op_sel_hi:[0,1,1]
	v_mov_b32_e32 v2, v35
	v_pk_fma_f32 v[0:1], v[4:5], v[2:3], v[0:1] op_sel_hi:[0,1,1]
	v_pk_add_f32 v[32:33], v[36:37], v[0:1]
	ds_read_b128 v[0:3], v86 offset:304
	v_mov_b32_e32 v29, v75
	v_mov_b32_e32 v4, v27
	s_waitcnt lgkmcnt(0)
	v_mov_b32_e32 v28, v0
	v_pk_mul_f32 v[28:29], v[24:25], v[28:29]
	v_mov_b32_e32 v0, v1
	v_mov_b32_e32 v1, v74
	v_pk_fma_f32 v[0:1], v[24:25], v[0:1], v[28:29] op_sel:[1,0,0] op_sel_hi:[0,1,1]
	v_mov_b32_e32 v28, v2
	v_mov_b32_e32 v29, v76
	v_pk_fma_f32 v[0:1], v[26:27], v[28:29], v[0:1] op_sel_hi:[0,1,1]
	v_mov_b32_e32 v76, v3
	v_pk_fma_f32 v[0:1], v[4:5], v[76:77], v[0:1] op_sel_hi:[0,1,1]
	v_pk_add_f32 v[66:67], v[38:39], v[0:1]
	ds_read_b128 v[0:3], v86 offset:560
	ds_read_b128 v[28:31], v86 offset:816
	s_waitcnt lgkmcnt(1)
	v_mov_b32_e32 v35, v1
	s_waitcnt lgkmcnt(0)
	v_mov_b32_e32 v34, v28
	v_pk_mul_f32 v[34:35], v[24:25], v[34:35]
	v_mov_b32_e32 v28, v29
	v_mov_b32_e32 v29, v0
	v_pk_fma_f32 v[0:1], v[24:25], v[28:29], v[34:35] op_sel:[1,0,0] op_sel_hi:[0,1,1]
	v_mov_b32_e32 v24, v30
	v_mov_b32_e32 v25, v2
	v_pk_fma_f32 v[0:1], v[26:27], v[24:25], v[0:1] op_sel_hi:[0,1,1]
	v_mov_b32_e32 v2, v31
	v_pk_fma_f32 v[0:1], v[4:5], v[2:3], v[0:1] op_sel_hi:[0,1,1]
	v_pk_add_f32 v[68:69], v[32:33], v[0:1]
	v_mov_b32_e32 v24, v190
	v_mov_b32_e32 v25, v191
	v_mov_b32_e32 v26, v192
	v_mov_b32_e32 v27, v193
	v_mov_b32_e32 v0, v186
	v_mov_b32_e32 v1, v187
	v_mov_b32_e32 v2, v188
	v_mov_b32_e32 v3, v189
	v_mov_b32_e32 v28, v182
	v_mov_b32_e32 v29, v183
	v_mov_b32_e32 v30, v184
	v_mov_b32_e32 v31, v185
	v_mov_b32_e32 v32, v178
	v_mov_b32_e32 v33, v179
	v_mov_b32_e32 v34, v180
	v_mov_b32_e32 v35, v181
	ds_read_b128 v[36:39], v86 offset:64
	ds_read_b128 v[62:65], v86 offset:320
	s_waitcnt lgkmcnt(1)
	v_mov_b32_e32 v71, v37
	s_waitcnt lgkmcnt(0)
	v_mov_b32_e32 v70, v62
	v_mov_b32_e32 v62, v63
	v_mov_b32_e32 v63, v36
	s_waitcnt vmcnt(0)
	v_pk_mul_f32 v[70:71], v[32:33], v[70:71]
	s_nop 0
	v_pk_fma_f32 v[36:37], v[32:33], v[62:63], v[70:71] op_sel:[1,0,0] op_sel_hi:[0,1,1]
	v_mov_b32_e32 v62, v64
	v_mov_b32_e32 v63, v38
	v_pk_fma_f32 v[36:37], v[34:35], v[62:63], v[36:37] op_sel_hi:[0,1,1]
	v_mov_b32_e32 v4, v35
	v_mov_b32_e32 v38, v65
	v_pk_fma_f32 v[36:37], v[4:5], v[38:39], v[36:37] op_sel_hi:[0,1,1]
	v_pk_add_f32 v[66:67], v[66:67], v[36:37]
	ds_read_b128 v[36:39], v86 offset:576
	ds_read_b128 v[62:65], v86 offset:832
	s_waitcnt lgkmcnt(1)
	v_mov_b32_e32 v71, v37
	s_waitcnt lgkmcnt(0)
; #define LAS __attribute__((address_space(3)))
; __device__ __forceinline__ void attn_sample_wave(const Frame& F, int unit) {
;     ...
;     for (int kk = 0; kk < 3; ++kk) { const int kidx = kk * 64 + lane;
; #pragma unroll
;         for (int t = 0; t < 4; ++t) sc[kk][t] = 0.f;
;         if (kidx < 128) { const f32x4* kr = (const f32x4*)(F.in[2] + ((size_t)b * 128 + kidx) * 256 + g * 64);
; #pragma unroll 8
;             for (int d4 = 0; d4 < 16; ++d4) { const f32x4 kv = kr[d4];
; #pragma unroll
;                 for (int t = 0; t < 4; ++t) { const f32x4 q = *(const LAS f32x4*)(sq + t * 64 + d4 * 4); sc[kk][t] += kv[0] * q[0] + kv[1] * q[1] + kv[2] * q[2] + kv[3] * q[3]; } } }
	v_mov_b32_e32 v70, v62
	v_pk_mul_f32 v[70:71], v[32:33], v[70:71]
	v_mov_b32_e32 v62, v63
	v_mov_b32_e32 v63, v36
	v_pk_fma_f32 v[32:33], v[32:33], v[62:63], v[70:71] op_sel:[1,0,0] op_sel_hi:[0,1,1]
	v_mov_b32_e32 v36, v64
	v_mov_b32_e32 v37, v38
	v_pk_fma_f32 v[32:33], v[34:35], v[36:37], v[32:33] op_sel_hi:[0,1,1]
	v_mov_b32_e32 v38, v65
	v_pk_fma_f32 v[32:33], v[4:5], v[38:39], v[32:33] op_sel_hi:[0,1,1]
	v_pk_add_f32 v[62:63], v[68:69], v[32:33]
	ds_read_b128 v[32:35], v86 offset:80
	ds_read_b128 v[36:39], v86 offset:336
	v_mov_b32_e32 v4, v31
	s_waitcnt lgkmcnt(1)
	v_mov_b32_e32 v65, v33
	s_waitcnt lgkmcnt(0)
	v_mov_b32_e32 v64, v36
	v_pk_mul_f32 v[64:65], v[28:29], v[64:65]
	v_mov_b32_e32 v36, v37
	v_mov_b32_e32 v37, v32
	v_pk_fma_f32 v[32:33], v[28:29], v[36:37], v[64:65] op_sel:[1,0,0] op_sel_hi:[0,1,1]
	v_mov_b32_e32 v36, v38
	v_mov_b32_e32 v37, v34
	v_pk_fma_f32 v[32:33], v[30:31], v[36:37], v[32:33] op_sel_hi:[0,1,1]
	v_mov_b32_e32 v34, v39
	v_pk_fma_f32 v[32:33], v[4:5], v[34:35], v[32:33] op_sel_hi:[0,1,1]
	v_pk_add_f32 v[64:65], v[66:67], v[32:33]
	ds_read_b128 v[32:35], v86 offset:592
	ds_read_b128 v[36:39], v86 offset:848
	s_waitcnt lgkmcnt(1)
	v_mov_b32_e32 v67, v33
	s_waitcnt lgkmcnt(0)
	v_mov_b32_e32 v66, v36
	v_pk_mul_f32 v[66:67], v[28:29], v[66:67]
	v_mov_b32_e32 v36, v37
	v_mov_b32_e32 v37, v32
	v_pk_fma_f32 v[28:29], v[28:29], v[36:37], v[66:67] op_sel:[1,0,0] op_sel_hi:[0,1,1]
	v_mov_b32_e32 v32, v38
	v_mov_b32_e32 v33, v34
	v_pk_fma_f32 v[28:29], v[30:31], v[32:33], v[28:29] op_sel_hi:[0,1,1]
	v_mov_b32_e32 v34, v39
	v_pk_fma_f32 v[28:29], v[4:5], v[34:35], v[28:29] op_sel_hi:[0,1,1]
	v_pk_add_f32 v[36:37], v[62:63], v[28:29]
	ds_read_b128 v[28:31], v86 offset:96
	ds_read_b128 v[32:35], v86 offset:352
	v_mov_b32_e32 v4, v3
	s_waitcnt lgkmcnt(1)
	v_mov_b32_e32 v39, v29
	s_waitcnt lgkmcnt(0)
	v_mov_b32_e32 v38, v32
	v_pk_mul_f32 v[38:39], v[0:1], v[38:39]
	v_mov_b32_e32 v32, v33
	v_mov_b32_e32 v33, v28
	v_pk_fma_f32 v[28:29], v[0:1], v[32:33], v[38:39] op_sel:[1,0,0] op_sel_hi:[0,1,1]
	v_mov_b32_e32 v32, v34
	v_mov_b32_e32 v33, v30
	v_pk_fma_f32 v[28:29], v[2:3], v[32:33], v[28:29] op_sel_hi:[0,1,1]
	v_mov_b32_e32 v30, v35
	v_pk_fma_f32 v[28:29], v[4:5], v[30:31], v[28:29] op_sel_hi:[0,1,1]
	v_pk_add_f32 v[38:39], v[64:65], v[28:29]
	ds_read_b128 v[28:31], v86 offset:608
	ds_read_b128 v[32:35], v86 offset:864
	s_waitcnt lgkmcnt(1)
	v_mov_b32_e32 v63, v29
	s_waitcnt lgkmcnt(0)
	v_mov_b32_e32 v62, v32
	v_pk_mul_f32 v[62:63], v[0:1], v[62:63]
	v_mov_b32_e32 v32, v33
	v_mov_b32_e32 v33, v28
	v_pk_fma_f32 v[0:1], v[0:1], v[32:33], v[62:63] op_sel:[1,0,0] op_sel_hi:[0,1,1]
	v_mov_b32_e32 v28, v34
	v_mov_b32_e32 v29, v30
	v_pk_fma_f32 v[0:1], v[2:3], v[28:29], v[0:1] op_sel_hi:[0,1,1]
	v_mov_b32_e32 v30, v35
	v_pk_fma_f32 v[0:1], v[4:5], v[30:31], v[0:1] op_sel_hi:[0,1,1]
	v_pk_add_f32 v[36:37], v[36:37], v[0:1]
	ds_read_b128 v[0:3], v86 offset:112
	ds_read_b128 v[28:31], v86 offset:368
	v_mov_b32_e32 v4, v27
	s_waitcnt lgkmcnt(1)
	v_mov_b32_e32 v33, v1
	s_waitcnt lgkmcnt(0)
	v_mov_b32_e32 v32, v28
	v_pk_mul_f32 v[32:33], v[24:25], v[32:33]
	v_mov_b32_e32 v28, v29
	v_mov_b32_e32 v29, v0
	v_pk_fma_f32 v[0:1], v[24:25], v[28:29], v[32:33] op_sel:[1,0,0] op_sel_hi:[0,1,1]
	v_mov_b32_e32 v28, v30
	v_mov_b32_e32 v29, v2
	v_pk_fma_f32 v[0:1], v[26:27], v[28:29], v[0:1] op_sel_hi:[0,1,1]
	v_mov_b32_e32 v2, v31
	ds_read_b128 v[28:31], v86 offset:624
	ds_read_b128 v[32:35], v86 offset:880
	v_pk_fma_f32 v[0:1], v[4:5], v[2:3], v[0:1] op_sel_hi:[0,1,1]
	v_pk_add_f32 v[2:3], v[38:39], v[0:1]
	s_waitcnt lgkmcnt(1)
	v_mov_b32_e32 v1, v29
	s_waitcnt lgkmcnt(0)
	v_mov_b32_e32 v0, v32
	v_pk_mul_f32 v[0:1], v[24:25], v[0:1]
	v_mov_b32_e32 v32, v33
	v_mov_b32_e32 v33, v28
	v_pk_fma_f32 v[0:1], v[24:25], v[32:33], v[0:1] op_sel:[1,0,0] op_sel_hi:[0,1,1]
	v_mov_b32_e32 v24, v34
	v_mov_b32_e32 v25, v30
	v_pk_fma_f32 v[0:1], v[26:27], v[24:25], v[0:1] op_sel_hi:[0,1,1]
	v_mov_b32_e32 v30, v35
	v_pk_fma_f32 v[0:1], v[4:5], v[30:31], v[0:1] op_sel_hi:[0,1,1]
	v_pk_add_f32 v[0:1], v[36:37], v[0:1]
	v_mov_b32_e32 v22, 0
	v_lshl_add_u64 v[24:25], v[18:19], 0, s[34:35]
	s_mov_b32 s28, 0
	v_mov_b32_e32 v23, v22
	v_mov_b32_e32 v26, v22
	v_mov_b32_e32 v27, v22
	global_load_dwordx4 v[100:103], v[24:25], off offset:-64
	global_load_dwordx4 v[104:107], v[24:25], off offset:-48
	global_load_dwordx4 v[108:111], v[24:25], off offset:-32
	global_load_dwordx4 v[112:115], v[24:25], off offset:-16
	global_load_dwordx4 v[116:119], v[24:25], off
	global_load_dwordx4 v[120:123], v[24:25], off offset:16
	global_load_dwordx4 v[124:127], v[24:25], off offset:32
	global_load_dwordx4 v[128:131], v[24:25], off offset:48
; #define LAS __attribute__((address_space(3)))
; __device__ __forceinline__ void attn_sample_wave(const Frame& F, int unit) {
;     ...
;     for (int kk = 0; kk < 3; ++kk) { const int kidx = kk * 64 + lane;
; #pragma unroll
;         for (int t = 0; t < 4; ++t) sc[kk][t] = 0.f;
;         if (kidx < 128) { const f32x4* kr = (const f32x4*)(F.in[2] + ((size_t)b * 128 + kidx) * 256 + g * 64);
; #pragma unroll 8
;             for (int d4 = 0; d4 < 16; ++d4) { const f32x4 kv = kr[d4];
; #pragma unroll
;                 for (int t = 0; t < 4; ++t) { const f32x4 q = *(const LAS f32x4*)(sq + t * 64 + d4 * 4); sc[kk][t] += kv[0] * q[0] + kv[1] * q[1] + kv[2] * q[2] + kv[3] * q[3]; } } }
.LBB0_512:
	s_waitcnt vmcnt(0)
	v_mov_b32_e32 v28, v112
	v_mov_b32_e32 v29, v113
	v_mov_b32_e32 v30, v114
	v_mov_b32_e32 v31, v115
	v_mov_b32_e32 v32, v108
	v_mov_b32_e32 v33, v109
	v_mov_b32_e32 v34, v110
	v_mov_b32_e32 v35, v111
	v_mov_b32_e32 v36, v104
	v_mov_b32_e32 v37, v105
	v_mov_b32_e32 v38, v106
	v_mov_b32_e32 v39, v107
	v_mov_b32_e32 v62, v100
	v_mov_b32_e32 v63, v101
	v_mov_b32_e32 v64, v102
	v_mov_b32_e32 v65, v103
	s_add_i32 s29, s90, s28
	v_mov_b32_e32 v4, s29
	ds_read_b128 v[66:69], v4
	ds_read_b128 v[70:73], v4 offset:16
	ds_read_b128 v[74:77], v4 offset:32
	ds_read_b128 v[78:81], v4 offset:48
	ds_read_b128 v[82:85], v4 offset:256
	s_waitcnt lgkmcnt(4)
	v_mov_b32_e32 v87, v67
	s_addk_i32 s28, 0x80
	s_mov_b64 s[42:43], 0x80
	s_cmpk_lg_i32 s28, 0x100
	s_waitcnt lgkmcnt(0)
	v_mov_b32_e32 v86, v82
	v_mov_b32_e32 v82, v83
	v_mov_b32_e32 v83, v66
	s_waitcnt vmcnt(0)
	v_pk_mul_f32 v[86:87], v[62:63], v[86:87]
	s_nop 0
	v_pk_fma_f32 v[66:67], v[62:63], v[82:83], v[86:87] op_sel:[1,0,0] op_sel_hi:[0,1,1]
	v_mov_b32_e32 v82, v84
	v_mov_b32_e32 v83, v68
	v_pk_fma_f32 v[66:67], v[64:65], v[82:83], v[66:67] op_sel_hi:[0,1,1]
	v_mov_b32_e32 v86, v65
	v_mov_b32_e32 v68, v85
	v_pk_fma_f32 v[66:67], v[86:87], v[68:69], v[66:67] op_sel_hi:[0,1,1]
	v_pk_add_f32 v[26:27], v[26:27], v[66:67]
	ds_read_b128 v[66:69], v4 offset:512
	ds_read_b128 v[82:85], v4 offset:768
	s_waitcnt lgkmcnt(1)
	v_mov_b32_e32 v89, v67
	s_waitcnt lgkmcnt(0)
	v_mov_b32_e32 v88, v82
	v_pk_mul_f32 v[88:89], v[62:63], v[88:89]
	v_mov_b32_e32 v82, v83
	v_mov_b32_e32 v83, v66
	v_pk_fma_f32 v[62:63], v[62:63], v[82:83], v[88:89] op_sel:[1,0,0] op_sel_hi:[0,1,1]
	v_mov_b32_e32 v66, v84
	v_mov_b32_e32 v67, v68
	v_pk_fma_f32 v[62:63], v[64:65], v[66:67], v[62:63] op_sel_hi:[0,1,1]
	v_mov_b32_e32 v68, v85
	v_pk_fma_f32 v[62:63], v[86:87], v[68:69], v[62:63] op_sel_hi:[0,1,1]
	v_pk_add_f32 v[22:23], v[22:23], v[62:63]
	ds_read_b128 v[62:65], v4 offset:272
	v_mov_b32_e32 v67, v71
	s_waitcnt lgkmcnt(0)
	v_mov_b32_e32 v66, v62
	v_pk_mul_f32 v[66:67], v[36:37], v[66:67]
	v_mov_b32_e32 v62, v63
	v_mov_b32_e32 v63, v70
	v_pk_fma_f32 v[62:63], v[36:37], v[62:63], v[66:67] op_sel:[1,0,0] op_sel_hi:[0,1,1]
	v_mov_b32_e32 v66, v64
	v_mov_b32_e32 v67, v72
	v_pk_fma_f32 v[62:63], v[38:39], v[66:67], v[62:63] op_sel_hi:[0,1,1]
	v_mov_b32_e32 v70, v39
	v_mov_b32_e32 v72, v65
	v_pk_fma_f32 v[62:63], v[70:71], v[72:73], v[62:63] op_sel_hi:[0,1,1]
	v_pk_add_f32 v[26:27], v[26:27], v[62:63]
	ds_read_b128 v[62:65], v4 offset:528
	ds_read_b128 v[66:69], v4 offset:784
	s_waitcnt lgkmcnt(1)
	v_mov_b32_e32 v73, v63
	s_waitcnt lgkmcnt(0)
	v_mov_b32_e32 v72, v66
	v_pk_mul_f32 v[72:73], v[36:37], v[72:73]
	v_mov_b32_e32 v66, v67
	v_mov_b32_e32 v67, v62
	v_pk_fma_f32 v[36:37], v[36:37], v[66:67], v[72:73] op_sel:[1,0,0] op_sel_hi:[0,1,1]
	v_mov_b32_e32 v62, v68
	v_mov_b32_e32 v63, v64
	v_pk_fma_f32 v[36:37], v[38:39], v[62:63], v[36:37] op_sel_hi:[0,1,1]
	v_mov_b32_e32 v64, v69
	v_pk_fma_f32 v[36:37], v[70:71], v[64:65], v[36:37] op_sel_hi:[0,1,1]
	v_pk_add_f32 v[22:23], v[22:23], v[36:37]
	ds_read_b128 v[36:39], v4 offset:288
	v_mov_b32_e32 v63, v75
	v_mov_b32_e32 v66, v35
	s_waitcnt lgkmcnt(0)
	v_mov_b32_e32 v62, v36
	v_pk_mul_f32 v[62:63], v[32:33], v[62:63]
	v_mov_b32_e32 v36, v37
	v_mov_b32_e32 v37, v74
	v_pk_fma_f32 v[36:37], v[32:33], v[36:37], v[62:63] op_sel:[1,0,0] op_sel_hi:[0,1,1]
	v_mov_b32_e32 v62, v38
	v_mov_b32_e32 v63, v76
	v_pk_fma_f32 v[36:37], v[34:35], v[62:63], v[36:37] op_sel_hi:[0,1,1]
	v_mov_b32_e32 v76, v39
	v_pk_fma_f32 v[36:37], v[66:67], v[76:77], v[36:37] op_sel_hi:[0,1,1]
	v_pk_add_f32 v[26:27], v[26:27], v[36:37]
	ds_read_b128 v[36:39], v4 offset:544
	ds_read_b128 v[62:65], v4 offset:800
	s_waitcnt lgkmcnt(1)
	v_mov_b32_e32 v69, v37
	s_waitcnt lgkmcnt(0)
	v_mov_b32_e32 v68, v62
	v_pk_mul_f32 v[68:69], v[32:33], v[68:69]
	v_mov_b32_e32 v62, v63
	v_mov_b32_e32 v63, v36
	v_pk_fma_f32 v[32:33], v[32:33], v[62:63], v[68:69] op_sel:[1,0,0] op_sel_hi:[0,1,1]
	v_mov_b32_e32 v36, v64
	v_mov_b32_e32 v37, v38
	v_pk_fma_f32 v[32:33], v[34:35], v[36:37], v[32:33] op_sel_hi:[0,1,1]
	v_mov_b32_e32 v38, v65
	v_pk_fma_f32 v[32:33], v[66:67], v[38:39], v[32:33] op_sel_hi:[0,1,1]
	v_pk_add_f32 v[62:63], v[22:23], v[32:33]
	ds_read_b128 v[32:35], v4 offset:304
	v_mov_b32_e32 v23, v79
	v_mov_b32_e32 v64, v31
	s_waitcnt lgkmcnt(0)
	v_mov_b32_e32 v22, v32
	v_pk_mul_f32 v[22:23], v[28:29], v[22:23]
	v_mov_b32_e32 v32, v33
	v_mov_b32_e32 v33, v78
	v_pk_fma_f32 v[22:23], v[28:29], v[32:33], v[22:23] op_sel:[1,0,0] op_sel_hi:[0,1,1]
	v_mov_b32_e32 v32, v34
	v_mov_b32_e32 v33, v80
	v_pk_fma_f32 v[22:23], v[30:31], v[32:33], v[22:23] op_sel_hi:[0,1,1]
	v_mov_b32_e32 v80, v35
	ds_read_b128 v[32:35], v4 offset:560
	ds_read_b128 v[36:39], v4 offset:816
	v_pk_fma_f32 v[22:23], v[64:65], v[80:81], v[22:23] op_sel_hi:[0,1,1]
	v_pk_add_f32 v[22:23], v[26:27], v[22:23]
	s_waitcnt lgkmcnt(1)
	v_mov_b32_e32 v27, v33
	s_waitcnt lgkmcnt(0)
	v_mov_b32_e32 v26, v36
	v_pk_mul_f32 v[26:27], v[28:29], v[26:27]
	v_mov_b32_e32 v36, v37
	v_mov_b32_e32 v37, v32
	v_pk_fma_f32 v[26:27], v[28:29], v[36:37], v[26:27] op_sel:[1,0,0] op_sel_hi:[0,1,1]
	v_mov_b32_e32 v28, v38
	v_mov_b32_e32 v29, v34
	v_pk_fma_f32 v[26:27], v[30:31], v[28:29], v[26:27] op_sel_hi:[0,1,1]
	v_mov_b32_e32 v34, v39
	v_pk_fma_f32 v[26:27], v[64:65], v[34:35], v[26:27] op_sel_hi:[0,1,1]
	v_pk_add_f32 v[26:27], v[62:63], v[26:27]
	v_mov_b32_e32 v28, v128
	v_mov_b32_e32 v29, v129
	v_mov_b32_e32 v30, v130
	v_mov_b32_e32 v31, v131
	v_mov_b32_e32 v32, v124
	v_mov_b32_e32 v33, v125
	v_mov_b32_e32 v34, v126
	v_mov_b32_e32 v35, v127
	v_mov_b32_e32 v36, v120
	v_mov_b32_e32 v37, v121
	v_mov_b32_e32 v38, v122
	v_mov_b32_e32 v39, v123
	v_mov_b32_e32 v62, v116
	v_mov_b32_e32 v63, v117
	v_mov_b32_e32 v64, v118
	v_mov_b32_e32 v65, v119
	ds_read_b128 v[66:69], v4 offset:64
	ds_read_b128 v[70:73], v4 offset:320
	v_lshl_add_u64 v[24:25], v[24:25], 0, s[42:43]
	s_waitcnt lgkmcnt(1)
; #define LAS __attribute__((address_space(3)))
; __device__ __forceinline__ void attn_sample_wave(const Frame& F, int unit) {
;     ...
;     for (int kk = 0; kk < 3; ++kk) { const int kidx = kk * 64 + lane;
; #pragma unroll
;         for (int t = 0; t < 4; ++t) sc[kk][t] = 0.f;
;         if (kidx < 128) { const f32x4* kr = (const f32x4*)(F.in[2] + ((size_t)b * 128 + kidx) * 256 + g * 64);
; #pragma unroll 8
;             for (int d4 = 0; d4 < 16; ++d4) { const f32x4 kv = kr[d4];
; #pragma unroll
;                 for (int t = 0; t < 4; ++t) { const f32x4 q = *(const LAS f32x4*)(sq + t * 64 + d4 * 4); sc[kk][t] += kv[0] * q[0] + kv[1] * q[1] + kv[2] * q[2] + kv[3] * q[3]; } } }
	v_mov_b32_e32 v75, v67
	s_waitcnt lgkmcnt(0)
	v_mov_b32_e32 v74, v70
	v_mov_b32_e32 v70, v71
	v_mov_b32_e32 v71, v66
	s_waitcnt vmcnt(0)
	v_pk_mul_f32 v[74:75], v[62:63], v[74:75]
	s_nop 0
	v_pk_fma_f32 v[66:67], v[62:63], v[70:71], v[74:75] op_sel:[1,0,0] op_sel_hi:[0,1,1]
	v_mov_b32_e32 v70, v72
	v_mov_b32_e32 v71, v68
	v_pk_fma_f32 v[66:67], v[64:65], v[70:71], v[66:67] op_sel_hi:[0,1,1]
	v_mov_b32_e32 v74, v65
	v_mov_b32_e32 v68, v73
	v_pk_fma_f32 v[66:67], v[74:75], v[68:69], v[66:67] op_sel_hi:[0,1,1]
	v_pk_add_f32 v[22:23], v[22:23], v[66:67]
	ds_read_b128 v[66:69], v4 offset:576
	ds_read_b128 v[70:73], v4 offset:832
	s_waitcnt lgkmcnt(1)
	v_mov_b32_e32 v77, v67
	s_waitcnt lgkmcnt(0)
	v_mov_b32_e32 v76, v70
	v_pk_mul_f32 v[76:77], v[62:63], v[76:77]
	v_mov_b32_e32 v70, v71
	v_mov_b32_e32 v71, v66
	v_pk_fma_f32 v[62:63], v[62:63], v[70:71], v[76:77] op_sel:[1,0,0] op_sel_hi:[0,1,1]
	v_mov_b32_e32 v66, v72
	v_mov_b32_e32 v67, v68
	v_pk_fma_f32 v[62:63], v[64:65], v[66:67], v[62:63] op_sel_hi:[0,1,1]
	v_mov_b32_e32 v68, v73
	v_pk_fma_f32 v[62:63], v[74:75], v[68:69], v[62:63] op_sel_hi:[0,1,1]
	v_pk_add_f32 v[26:27], v[26:27], v[62:63]
	ds_read_b128 v[62:65], v4 offset:80
	ds_read_b128 v[66:69], v4 offset:336
	s_waitcnt lgkmcnt(1)
	v_mov_b32_e32 v71, v63
	s_waitcnt lgkmcnt(0)
	v_mov_b32_e32 v70, v66
	v_pk_mul_f32 v[70:71], v[36:37], v[70:71]
	v_mov_b32_e32 v66, v67
	v_mov_b32_e32 v67, v62
	v_pk_fma_f32 v[62:63], v[36:37], v[66:67], v[70:71] op_sel:[1,0,0] op_sel_hi:[0,1,1]
	v_mov_b32_e32 v66, v68
	v_mov_b32_e32 v67, v64
	v_pk_fma_f32 v[62:63], v[38:39], v[66:67], v[62:63] op_sel_hi:[0,1,1]
	v_mov_b32_e32 v70, v39
	v_mov_b32_e32 v64, v69
	v_pk_fma_f32 v[62:63], v[70:71], v[64:65], v[62:63] op_sel_hi:[0,1,1]
	v_pk_add_f32 v[22:23], v[22:23], v[62:63]
	ds_read_b128 v[62:65], v4 offset:592
	ds_read_b128 v[66:69], v4 offset:848
	s_waitcnt lgkmcnt(1)
	v_mov_b32_e32 v73, v63
	s_waitcnt lgkmcnt(0)
	v_mov_b32_e32 v72, v66
	v_pk_mul_f32 v[72:73], v[36:37], v[72:73]
	v_mov_b32_e32 v66, v67
	v_mov_b32_e32 v67, v62
	v_pk_fma_f32 v[36:37], v[36:37], v[66:67], v[72:73] op_sel:[1,0,0] op_sel_hi:[0,1,1]
	v_mov_b32_e32 v62, v68
	v_mov_b32_e32 v63, v64
	v_pk_fma_f32 v[36:37], v[38:39], v[62:63], v[36:37] op_sel_hi:[0,1,1]
	v_mov_b32_e32 v64, v69
	v_pk_fma_f32 v[36:37], v[70:71], v[64:65], v[36:37] op_sel_hi:[0,1,1]
	v_pk_add_f32 v[26:27], v[26:27], v[36:37]
	ds_read_b128 v[36:39], v4 offset:96
	ds_read_b128 v[62:65], v4 offset:352
	s_waitcnt lgkmcnt(1)
	v_mov_b32_e32 v67, v37
	s_waitcnt lgkmcnt(0)
	v_mov_b32_e32 v66, v62
	v_pk_mul_f32 v[66:67], v[32:33], v[66:67]
	v_mov_b32_e32 v62, v63
	v_mov_b32_e32 v63, v36
	v_pk_fma_f32 v[36:37], v[32:33], v[62:63], v[66:67] op_sel:[1,0,0] op_sel_hi:[0,1,1]
	v_mov_b32_e32 v62, v64
	v_mov_b32_e32 v63, v38
	v_pk_fma_f32 v[36:37], v[34:35], v[62:63], v[36:37] op_sel_hi:[0,1,1]
	v_mov_b32_e32 v66, v35
	v_mov_b32_e32 v38, v65
	v_pk_fma_f32 v[36:37], v[66:67], v[38:39], v[36:37] op_sel_hi:[0,1,1]
	v_pk_add_f32 v[22:23], v[22:23], v[36:37]
	ds_read_b128 v[36:39], v4 offset:608
	ds_read_b128 v[62:65], v4 offset:864
	s_waitcnt lgkmcnt(1)
	v_mov_b32_e32 v69, v37
	s_waitcnt lgkmcnt(0)
	v_mov_b32_e32 v68, v62
	v_pk_mul_f32 v[68:69], v[32:33], v[68:69]
	v_mov_b32_e32 v62, v63
	v_mov_b32_e32 v63, v36
	v_pk_fma_f32 v[32:33], v[32:33], v[62:63], v[68:69] op_sel:[1,0,0] op_sel_hi:[0,1,1]
	v_mov_b32_e32 v36, v64
	v_mov_b32_e32 v37, v38
	v_pk_fma_f32 v[32:33], v[34:35], v[36:37], v[32:33] op_sel_hi:[0,1,1]
	v_mov_b32_e32 v38, v65
	v_pk_fma_f32 v[32:33], v[66:67], v[38:39], v[32:33] op_sel_hi:[0,1,1]
	v_pk_add_f32 v[62:63], v[26:27], v[32:33]
	ds_read_b128 v[32:35], v4 offset:112
	ds_read_b128 v[36:39], v4 offset:368
	v_mov_b32_e32 v64, v31
	s_waitcnt lgkmcnt(1)
	v_mov_b32_e32 v27, v33
	s_waitcnt lgkmcnt(0)
	v_mov_b32_e32 v26, v36
	v_pk_mul_f32 v[26:27], v[28:29], v[26:27]
	v_mov_b32_e32 v36, v37
	v_mov_b32_e32 v37, v32
	v_pk_fma_f32 v[26:27], v[28:29], v[36:37], v[26:27] op_sel:[1,0,0] op_sel_hi:[0,1,1]
	v_mov_b32_e32 v32, v38
	v_mov_b32_e32 v33, v34
	v_pk_fma_f32 v[26:27], v[30:31], v[32:33], v[26:27] op_sel_hi:[0,1,1]
	v_mov_b32_e32 v34, v39
	v_pk_fma_f32 v[26:27], v[64:65], v[34:35], v[26:27] op_sel_hi:[0,1,1]
	ds_read_b128 v[32:35], v4 offset:624
	ds_read_b128 v[36:39], v4 offset:880
	v_pk_add_f32 v[26:27], v[22:23], v[26:27]
	s_waitcnt lgkmcnt(1)
	v_mov_b32_e32 v23, v33
	s_waitcnt lgkmcnt(0)
	v_mov_b32_e32 v22, v36
	v_pk_mul_f32 v[22:23], v[28:29], v[22:23]
	v_mov_b32_e32 v36, v37
	v_mov_b32_e32 v37, v32
	v_pk_fma_f32 v[22:23], v[28:29], v[36:37], v[22:23] op_sel:[1,0,0] op_sel_hi:[0,1,1]
	v_mov_b32_e32 v28, v38
	v_mov_b32_e32 v29, v34
	v_pk_fma_f32 v[22:23], v[30:31], v[28:29], v[22:23] op_sel_hi:[0,1,1]
	v_mov_b32_e32 v34, v39
	v_pk_fma_f32 v[22:23], v[64:65], v[34:35], v[22:23] op_sel_hi:[0,1,1]
	v_pk_add_f32 v[22:23], v[62:63], v[22:23]
	global_load_dwordx4 v[28:31], v[24:25], off offset:-16
	global_load_dwordx4 v[32:35], v[24:25], off offset:-32
	global_load_dwordx4 v[36:39], v[24:25], off offset:-48
	global_load_dwordx4 v[62:65], v[24:25], off offset:-64
	s_add_i32 s29, s90, s28
	v_mov_b32_e32 v4, s29
	ds_read_b128 v[66:69], v4
	ds_read_b128 v[70:73], v4 offset:16
	ds_read_b128 v[74:77], v4 offset:32
	ds_read_b128 v[78:81], v4 offset:48
	ds_read_b128 v[82:85], v4 offset:256
	s_waitcnt lgkmcnt(4)
	v_mov_b32_e32 v87, v67
	s_addk_i32 s28, 0x80
	s_mov_b64 s[42:43], 0x80
	s_cmpk_lg_i32 s28, 0x100
	s_waitcnt lgkmcnt(0)
	v_mov_b32_e32 v86, v82
	v_mov_b32_e32 v82, v83
	v_mov_b32_e32 v83, v66
	s_waitcnt vmcnt(0)
; #define LAS __attribute__((address_space(3)))
; __device__ __forceinline__ void attn_sample_wave(const Frame& F, int unit) {
;     ...
;     for (int kk = 0; kk < 3; ++kk) { const int kidx = kk * 64 + lane;
; #pragma unroll
;         for (int t = 0; t < 4; ++t) sc[kk][t] = 0.f;
;         if (kidx < 128) { const f32x4* kr = (const f32x4*)(F.in[2] + ((size_t)b * 128 + kidx) * 256 + g * 64);
; #pragma unroll 8
;             for (int d4 = 0; d4 < 16; ++d4) { const f32x4 kv = kr[d4];
; #pragma unroll
;                 for (int t = 0; t < 4; ++t) { const f32x4 q = *(const LAS f32x4*)(sq + t * 64 + d4 * 4); sc[kk][t] += kv[0] * q[0] + kv[1] * q[1] + kv[2] * q[2] + kv[3] * q[3]; } } }
	v_pk_mul_f32 v[86:87], v[62:63], v[86:87]
	s_nop 0
	v_pk_fma_f32 v[66:67], v[62:63], v[82:83], v[86:87] op_sel:[1,0,0] op_sel_hi:[0,1,1]
	v_mov_b32_e32 v82, v84
	v_mov_b32_e32 v83, v68
	v_pk_fma_f32 v[66:67], v[64:65], v[82:83], v[66:67] op_sel_hi:[0,1,1]
	v_mov_b32_e32 v86, v65
	v_mov_b32_e32 v68, v85
	v_pk_fma_f32 v[66:67], v[86:87], v[68:69], v[66:67] op_sel_hi:[0,1,1]
	v_pk_add_f32 v[26:27], v[26:27], v[66:67]
	ds_read_b128 v[66:69], v4 offset:512
	ds_read_b128 v[82:85], v4 offset:768
	s_waitcnt lgkmcnt(1)
	v_mov_b32_e32 v89, v67
	s_waitcnt lgkmcnt(0)
	v_mov_b32_e32 v88, v82
	v_pk_mul_f32 v[88:89], v[62:63], v[88:89]
	v_mov_b32_e32 v82, v83
	v_mov_b32_e32 v83, v66
	v_pk_fma_f32 v[62:63], v[62:63], v[82:83], v[88:89] op_sel:[1,0,0] op_sel_hi:[0,1,1]
	v_mov_b32_e32 v66, v84
	v_mov_b32_e32 v67, v68
	v_pk_fma_f32 v[62:63], v[64:65], v[66:67], v[62:63] op_sel_hi:[0,1,1]
	v_mov_b32_e32 v68, v85
	v_pk_fma_f32 v[62:63], v[86:87], v[68:69], v[62:63] op_sel_hi:[0,1,1]
	v_pk_add_f32 v[22:23], v[22:23], v[62:63]
	ds_read_b128 v[62:65], v4 offset:272
	v_mov_b32_e32 v67, v71
	s_waitcnt lgkmcnt(0)
	v_mov_b32_e32 v66, v62
	v_pk_mul_f32 v[66:67], v[36:37], v[66:67]
	v_mov_b32_e32 v62, v63
	v_mov_b32_e32 v63, v70
	v_pk_fma_f32 v[62:63], v[36:37], v[62:63], v[66:67] op_sel:[1,0,0] op_sel_hi:[0,1,1]
	v_mov_b32_e32 v66, v64
	v_mov_b32_e32 v67, v72
	v_pk_fma_f32 v[62:63], v[38:39], v[66:67], v[62:63] op_sel_hi:[0,1,1]
	v_mov_b32_e32 v70, v39
	v_mov_b32_e32 v72, v65
	v_pk_fma_f32 v[62:63], v[70:71], v[72:73], v[62:63] op_sel_hi:[0,1,1]
	v_pk_add_f32 v[26:27], v[26:27], v[62:63]
	ds_read_b128 v[62:65], v4 offset:528
	ds_read_b128 v[66:69], v4 offset:784
	s_waitcnt lgkmcnt(1)
	v_mov_b32_e32 v73, v63
	s_waitcnt lgkmcnt(0)
	v_mov_b32_e32 v72, v66
	v_pk_mul_f32 v[72:73], v[36:37], v[72:73]
	v_mov_b32_e32 v66, v67
	v_mov_b32_e32 v67, v62
	v_pk_fma_f32 v[36:37], v[36:37], v[66:67], v[72:73] op_sel:[1,0,0] op_sel_hi:[0,1,1]
	v_mov_b32_e32 v62, v68
	v_mov_b32_e32 v63, v64
	v_pk_fma_f32 v[36:37], v[38:39], v[62:63], v[36:37] op_sel_hi:[0,1,1]
	v_mov_b32_e32 v64, v69
	v_pk_fma_f32 v[36:37], v[70:71], v[64:65], v[36:37] op_sel_hi:[0,1,1]
	v_pk_add_f32 v[22:23], v[22:23], v[36:37]
	ds_read_b128 v[36:39], v4 offset:288
	v_mov_b32_e32 v63, v75
	v_mov_b32_e32 v66, v35
	s_waitcnt lgkmcnt(0)
	v_mov_b32_e32 v62, v36
	v_pk_mul_f32 v[62:63], v[32:33], v[62:63]
	v_mov_b32_e32 v36, v37
	v_mov_b32_e32 v37, v74
	v_pk_fma_f32 v[36:37], v[32:33], v[36:37], v[62:63] op_sel:[1,0,0] op_sel_hi:[0,1,1]
	v_mov_b32_e32 v62, v38
	v_mov_b32_e32 v63, v76
	v_pk_fma_f32 v[36:37], v[34:35], v[62:63], v[36:37] op_sel_hi:[0,1,1]
	v_mov_b32_e32 v76, v39
	v_pk_fma_f32 v[36:37], v[66:67], v[76:77], v[36:37] op_sel_hi:[0,1,1]
	v_pk_add_f32 v[26:27], v[26:27], v[36:37]
	ds_read_b128 v[36:39], v4 offset:544
	ds_read_b128 v[62:65], v4 offset:800
	s_waitcnt lgkmcnt(1)
	v_mov_b32_e32 v69, v37
	s_waitcnt lgkmcnt(0)
	v_mov_b32_e32 v68, v62
	v_pk_mul_f32 v[68:69], v[32:33], v[68:69]
	v_mov_b32_e32 v62, v63
	v_mov_b32_e32 v63, v36
	v_pk_fma_f32 v[32:33], v[32:33], v[62:63], v[68:69] op_sel:[1,0,0] op_sel_hi:[0,1,1]
	v_mov_b32_e32 v36, v64
	v_mov_b32_e32 v37, v38
	v_pk_fma_f32 v[32:33], v[34:35], v[36:37], v[32:33] op_sel_hi:[0,1,1]
	v_mov_b32_e32 v38, v65
	v_pk_fma_f32 v[32:33], v[66:67], v[38:39], v[32:33] op_sel_hi:[0,1,1]
	v_pk_add_f32 v[62:63], v[22:23], v[32:33]
	ds_read_b128 v[32:35], v4 offset:304
	v_mov_b32_e32 v23, v79
	v_mov_b32_e32 v64, v31
	s_waitcnt lgkmcnt(0)
	v_mov_b32_e32 v22, v32
	v_pk_mul_f32 v[22:23], v[28:29], v[22:23]
	v_mov_b32_e32 v32, v33
	v_mov_b32_e32 v33, v78
	v_pk_fma_f32 v[22:23], v[28:29], v[32:33], v[22:23] op_sel:[1,0,0] op_sel_hi:[0,1,1]
	v_mov_b32_e32 v32, v34
	v_mov_b32_e32 v33, v80
	v_pk_fma_f32 v[22:23], v[30:31], v[32:33], v[22:23] op_sel_hi:[0,1,1]
	v_mov_b32_e32 v80, v35
	ds_read_b128 v[32:35], v4 offset:560
	ds_read_b128 v[36:39], v4 offset:816
	v_pk_fma_f32 v[22:23], v[64:65], v[80:81], v[22:23] op_sel_hi:[0,1,1]
	v_pk_add_f32 v[22:23], v[26:27], v[22:23]
	s_waitcnt lgkmcnt(1)
	v_mov_b32_e32 v27, v33
	s_waitcnt lgkmcnt(0)
	v_mov_b32_e32 v26, v36
	v_pk_mul_f32 v[26:27], v[28:29], v[26:27]
	v_mov_b32_e32 v36, v37
	v_mov_b32_e32 v37, v32
	v_pk_fma_f32 v[26:27], v[28:29], v[36:37], v[26:27] op_sel:[1,0,0] op_sel_hi:[0,1,1]
	v_mov_b32_e32 v28, v38
	v_mov_b32_e32 v29, v34
	v_pk_fma_f32 v[26:27], v[30:31], v[28:29], v[26:27] op_sel_hi:[0,1,1]
	v_mov_b32_e32 v34, v39
	v_pk_fma_f32 v[26:27], v[64:65], v[34:35], v[26:27] op_sel_hi:[0,1,1]
	v_pk_add_f32 v[26:27], v[62:63], v[26:27]
	global_load_dwordx4 v[28:31], v[24:25], off offset:48
	global_load_dwordx4 v[32:35], v[24:25], off offset:32
	global_load_dwordx4 v[36:39], v[24:25], off offset:16
	global_load_dwordx4 v[62:65], v[24:25], off
	ds_read_b128 v[66:69], v4 offset:64
	ds_read_b128 v[70:73], v4 offset:320
	v_lshl_add_u64 v[24:25], v[24:25], 0, s[42:43]
	s_waitcnt lgkmcnt(1)
	v_mov_b32_e32 v75, v67
	s_waitcnt lgkmcnt(0)
	v_mov_b32_e32 v74, v70
	v_mov_b32_e32 v70, v71
	v_mov_b32_e32 v71, v66
	s_waitcnt vmcnt(0)
; #define LAS __attribute__((address_space(3)))
; __device__ __forceinline__ void attn_sample_wave(const Frame& F, int unit) {
;     ...
;     for (int kk = 0; kk < 3; ++kk) { const int kidx = kk * 64 + lane;
; #pragma unroll
;         for (int t = 0; t < 4; ++t) sc[kk][t] = 0.f;
;         if (kidx < 128) { const f32x4* kr = (const f32x4*)(F.in[2] + ((size_t)b * 128 + kidx) * 256 + g * 64);
; #pragma unroll 8
;             for (int d4 = 0; d4 < 16; ++d4) { const f32x4 kv = kr[d4];
; #pragma unroll
;                 for (int t = 0; t < 4; ++t) { const f32x4 q = *(const LAS f32x4*)(sq + t * 64 + d4 * 4); sc[kk][t] += kv[0] * q[0] + kv[1] * q[1] + kv[2] * q[2] + kv[3] * q[3]; } } }
	v_pk_mul_f32 v[74:75], v[62:63], v[74:75]
	s_nop 0
	v_pk_fma_f32 v[66:67], v[62:63], v[70:71], v[74:75] op_sel:[1,0,0] op_sel_hi:[0,1,1]
	v_mov_b32_e32 v70, v72
	v_mov_b32_e32 v71, v68
	v_pk_fma_f32 v[66:67], v[64:65], v[70:71], v[66:67] op_sel_hi:[0,1,1]
	v_mov_b32_e32 v74, v65
	v_mov_b32_e32 v68, v73
	v_pk_fma_f32 v[66:67], v[74:75], v[68:69], v[66:67] op_sel_hi:[0,1,1]
	v_pk_add_f32 v[22:23], v[22:23], v[66:67]
	ds_read_b128 v[66:69], v4 offset:576
	ds_read_b128 v[70:73], v4 offset:832
	s_waitcnt lgkmcnt(1)
	v_mov_b32_e32 v77, v67
	s_waitcnt lgkmcnt(0)
	v_mov_b32_e32 v76, v70
	v_pk_mul_f32 v[76:77], v[62:63], v[76:77]
	v_mov_b32_e32 v70, v71
	v_mov_b32_e32 v71, v66
	v_pk_fma_f32 v[62:63], v[62:63], v[70:71], v[76:77] op_sel:[1,0,0] op_sel_hi:[0,1,1]
	v_mov_b32_e32 v66, v72
	v_mov_b32_e32 v67, v68
	v_pk_fma_f32 v[62:63], v[64:65], v[66:67], v[62:63] op_sel_hi:[0,1,1]
	v_mov_b32_e32 v68, v73
	v_pk_fma_f32 v[62:63], v[74:75], v[68:69], v[62:63] op_sel_hi:[0,1,1]
	v_pk_add_f32 v[26:27], v[26:27], v[62:63]
	ds_read_b128 v[62:65], v4 offset:80
	ds_read_b128 v[66:69], v4 offset:336
	s_waitcnt lgkmcnt(1)
	v_mov_b32_e32 v71, v63
	s_waitcnt lgkmcnt(0)
	v_mov_b32_e32 v70, v66
	v_pk_mul_f32 v[70:71], v[36:37], v[70:71]
	v_mov_b32_e32 v66, v67
	v_mov_b32_e32 v67, v62
	v_pk_fma_f32 v[62:63], v[36:37], v[66:67], v[70:71] op_sel:[1,0,0] op_sel_hi:[0,1,1]
	v_mov_b32_e32 v66, v68
	v_mov_b32_e32 v67, v64
	v_pk_fma_f32 v[62:63], v[38:39], v[66:67], v[62:63] op_sel_hi:[0,1,1]
	v_mov_b32_e32 v70, v39
	v_mov_b32_e32 v64, v69
	v_pk_fma_f32 v[62:63], v[70:71], v[64:65], v[62:63] op_sel_hi:[0,1,1]
	v_pk_add_f32 v[22:23], v[22:23], v[62:63]
	ds_read_b128 v[62:65], v4 offset:592
	ds_read_b128 v[66:69], v4 offset:848
	s_waitcnt lgkmcnt(1)
	v_mov_b32_e32 v73, v63
	s_waitcnt lgkmcnt(0)
	v_mov_b32_e32 v72, v66
	v_pk_mul_f32 v[72:73], v[36:37], v[72:73]
	v_mov_b32_e32 v66, v67
	v_mov_b32_e32 v67, v62
	v_pk_fma_f32 v[36:37], v[36:37], v[66:67], v[72:73] op_sel:[1,0,0] op_sel_hi:[0,1,1]
	v_mov_b32_e32 v62, v68
	v_mov_b32_e32 v63, v64
	v_pk_fma_f32 v[36:37], v[38:39], v[62:63], v[36:37] op_sel_hi:[0,1,1]
	v_mov_b32_e32 v64, v69
	v_pk_fma_f32 v[36:37], v[70:71], v[64:65], v[36:37] op_sel_hi:[0,1,1]
	v_pk_add_f32 v[26:27], v[26:27], v[36:37]
	ds_read_b128 v[36:39], v4 offset:96
	ds_read_b128 v[62:65], v4 offset:352
	s_waitcnt lgkmcnt(1)
	v_mov_b32_e32 v67, v37
	s_waitcnt lgkmcnt(0)
	v_mov_b32_e32 v66, v62
	v_pk_mul_f32 v[66:67], v[32:33], v[66:67]
	v_mov_b32_e32 v62, v63
	v_mov_b32_e32 v63, v36
	v_pk_fma_f32 v[36:37], v[32:33], v[62:63], v[66:67] op_sel:[1,0,0] op_sel_hi:[0,1,1]
	v_mov_b32_e32 v62, v64
	v_mov_b32_e32 v63, v38
	v_pk_fma_f32 v[36:37], v[34:35], v[62:63], v[36:37] op_sel_hi:[0,1,1]
	v_mov_b32_e32 v66, v35
	v_mov_b32_e32 v38, v65
	v_pk_fma_f32 v[36:37], v[66:67], v[38:39], v[36:37] op_sel_hi:[0,1,1]
	v_pk_add_f32 v[22:23], v[22:23], v[36:37]
	ds_read_b128 v[36:39], v4 offset:608
	ds_read_b128 v[62:65], v4 offset:864
	s_waitcnt lgkmcnt(1)
	v_mov_b32_e32 v69, v37
	s_waitcnt lgkmcnt(0)
	v_mov_b32_e32 v68, v62
	v_pk_mul_f32 v[68:69], v[32:33], v[68:69]
	v_mov_b32_e32 v62, v63
	v_mov_b32_e32 v63, v36
	v_pk_fma_f32 v[32:33], v[32:33], v[62:63], v[68:69] op_sel:[1,0,0] op_sel_hi:[0,1,1]
	v_mov_b32_e32 v36, v64
	v_mov_b32_e32 v37, v38
	v_pk_fma_f32 v[32:33], v[34:35], v[36:37], v[32:33] op_sel_hi:[0,1,1]
	v_mov_b32_e32 v38, v65
	v_pk_fma_f32 v[32:33], v[66:67], v[38:39], v[32:33] op_sel_hi:[0,1,1]
	v_pk_add_f32 v[62:63], v[26:27], v[32:33]
	ds_read_b128 v[32:35], v4 offset:112
	ds_read_b128 v[36:39], v4 offset:368
	v_mov_b32_e32 v64, v31
	s_waitcnt lgkmcnt(1)
	v_mov_b32_e32 v27, v33
	s_waitcnt lgkmcnt(0)
	v_mov_b32_e32 v26, v36
	v_pk_mul_f32 v[26:27], v[28:29], v[26:27]
	v_mov_b32_e32 v36, v37
	v_mov_b32_e32 v37, v32
	v_pk_fma_f32 v[26:27], v[28:29], v[36:37], v[26:27] op_sel:[1,0,0] op_sel_hi:[0,1,1]
	v_mov_b32_e32 v32, v38
	v_mov_b32_e32 v33, v34
	v_pk_fma_f32 v[26:27], v[30:31], v[32:33], v[26:27] op_sel_hi:[0,1,1]
	v_mov_b32_e32 v34, v39
	v_pk_fma_f32 v[26:27], v[64:65], v[34:35], v[26:27] op_sel_hi:[0,1,1]
	ds_read_b128 v[32:35], v4 offset:624
	ds_read_b128 v[36:39], v4 offset:880
	v_pk_add_f32 v[26:27], v[22:23], v[26:27]
	s_waitcnt lgkmcnt(1)
	v_mov_b32_e32 v23, v33
	s_waitcnt lgkmcnt(0)
	v_mov_b32_e32 v22, v36
	v_pk_mul_f32 v[22:23], v[28:29], v[22:23]
	v_mov_b32_e32 v36, v37
	v_mov_b32_e32 v37, v32
	v_pk_fma_f32 v[22:23], v[28:29], v[36:37], v[22:23] op_sel:[1,0,0] op_sel_hi:[0,1,1]
	v_mov_b32_e32 v28, v38
	v_mov_b32_e32 v29, v34
	v_pk_fma_f32 v[22:23], v[30:31], v[28:29], v[22:23] op_sel_hi:[0,1,1]
	v_mov_b32_e32 v34, v39
	v_pk_fma_f32 v[22:23], v[64:65], v[34:35], v[22:23] op_sel_hi:[0,1,1]
	v_pk_add_f32 v[22:23], v[62:63], v[22:23]
	v_mov_b32_e32 v29, 0
	v_mov_b32_e32 v28, v29
	v_mov_b32_e32 v25, v29
	v_mov_b32_e32 v24, v29
	s_and_saveexec_b64 s[46:47], s[12:13]
	s_cbranch_execz .LBB0_516
	v_mov_b32_e32 v24, 0
	s_mov_b32 s28, 0
	v_mov_b32_e32 v25, v24
	v_mov_b32_e32 v28, v24
	v_mov_b32_e32 v29, v24
